# grid-barrier spin loops poll without s_sleep
# baseline (speedup 1.0000x reference)
.LBB0_89:
	global_load_dword v15, v172, s[8:9] sc1
	s_waitcnt lgkmcnt(0)
	global_load_dword v0, v172, s[10:11] sc1
	global_load_dword v1, v172, s[12:13] sc1
	global_load_dword v2, v172, s[14:15] sc1
	global_load_dword v3, v172, s[16:17] sc1
	global_load_dword v4, v172, s[18:19] sc1
	global_load_dword v5, v172, s[20:21] sc1
	global_load_dword v6, v172, s[22:23] sc1
	global_load_dword v7, v172, s[24:25] sc1
	global_load_dword v8, v172, s[26:27] sc1
	global_load_dword v9, v172, s[28:29] sc1
	global_load_dword v10, v172, s[30:31] sc1
	global_load_dword v11, v172, s[34:35] sc1
	global_load_dword v12, v172, s[36:37] sc1
	global_load_dword v13, v172, s[38:39] sc1
	global_load_dword v14, v172, s[40:41] sc1
	s_mov_b64 s[42:43], -1
	s_mov_b64 s[44:45], -1
	s_waitcnt vmcnt(14)
	v_add_u32_e32 v16, v0, v15
	s_waitcnt vmcnt(13)
	v_add_u32_e32 v16, v16, v1
	s_waitcnt vmcnt(12)
	v_add_u32_e32 v16, v16, v2
	s_waitcnt vmcnt(11)
	v_add_u32_e32 v16, v16, v3
	s_waitcnt vmcnt(10)
	v_add_u32_e32 v16, v16, v4
	s_waitcnt vmcnt(9)
	v_add_u32_e32 v16, v16, v5
	s_waitcnt vmcnt(8)
	v_add_u32_e32 v16, v16, v6
	s_waitcnt vmcnt(7)
	v_add_u32_e32 v16, v16, v7
	s_waitcnt vmcnt(6)
	v_add_u32_e32 v16, v16, v8
	s_waitcnt vmcnt(5)
	v_add_u32_e32 v16, v16, v9
	s_waitcnt vmcnt(4)
	v_add_u32_e32 v16, v16, v10
	s_waitcnt vmcnt(3)
	v_add_u32_e32 v16, v16, v11
	s_waitcnt vmcnt(2)
	v_add_u32_e32 v16, v16, v12
	s_waitcnt vmcnt(1)
	v_add_u32_e32 v16, v16, v13
	s_waitcnt vmcnt(0)
	v_add_u32_e32 v16, v16, v14
	v_cmp_eq_u32_e32 vcc, s57, v16
	s_cbranch_vccnz .LBB0_88
	s_and_b32 s42, s48, 0xff
	s_cmp_eq_u32 s42, 0
	s_mov_b64 s[42:43], -1
	s_mov_b64 s[46:47], -1
	s_nop 0
	s_cbranch_scc1 .LBB0_93
	s_and_b64 vcc, exec, s[46:47]
	s_cbranch_vccz .LBB0_88

.LBB0_107:
	s_and_b32 s22, s26, 0xff
	s_mov_b64 s[20:21], -1
	s_cmp_lg_u32 s22, 0
	s_mov_b64 s[24:25], -1
	s_nop 0
	s_cbranch_scc0 .LBB0_110
	s_and_b64 vcc, exec, s[24:25]
	s_cbranch_vccz .LBB0_106

.LBB0_124:
	s_and_b32 s20, s24, 0xff
	s_mov_b64 s[18:19], -1
	s_cmp_lg_u32 s20, 0
	s_mov_b64 s[22:23], -1
	s_nop 0
	s_cbranch_scc0 .LBB0_127
	s_and_b64 vcc, exec, s[22:23]
	s_cbranch_vccz .LBB0_123

.LBB0_236:
	global_load_dword v15, v172, s[6:7] sc1
	s_waitcnt lgkmcnt(0)
	global_load_dword v0, v172, s[8:9] sc1
	global_load_dword v1, v172, s[10:11] sc1
	global_load_dword v2, v172, s[12:13] sc1
	global_load_dword v3, v172, s[14:15] sc1
	global_load_dword v4, v172, s[16:17] sc1
	global_load_dword v5, v172, s[18:19] sc1
	global_load_dword v6, v172, s[20:21] sc1
	global_load_dword v7, v172, s[22:23] sc1
	global_load_dword v8, v172, s[24:25] sc1
	global_load_dword v9, v172, s[26:27] sc1
	global_load_dword v10, v172, s[28:29] sc1
	global_load_dword v11, v172, s[30:31] sc1
	global_load_dword v12, v172, s[34:35] sc1
	global_load_dword v13, v172, s[36:37] sc1
	global_load_dword v14, v172, s[38:39] sc1
	s_mov_b64 s[40:41], -1
	s_mov_b64 s[42:43], -1
	s_waitcnt vmcnt(14)
	v_add_u32_e32 v16, v0, v15
	s_waitcnt vmcnt(13)
	v_add_u32_e32 v16, v16, v1
	s_waitcnt vmcnt(12)
	v_add_u32_e32 v16, v16, v2
	s_waitcnt vmcnt(11)
	v_add_u32_e32 v16, v16, v3
	s_waitcnt vmcnt(10)
	v_add_u32_e32 v16, v16, v4
	s_waitcnt vmcnt(9)
	v_add_u32_e32 v16, v16, v5
	s_waitcnt vmcnt(8)
	v_add_u32_e32 v16, v16, v6
	s_waitcnt vmcnt(7)
	v_add_u32_e32 v16, v16, v7
	s_waitcnt vmcnt(6)
	v_add_u32_e32 v16, v16, v8
	s_waitcnt vmcnt(5)
	v_add_u32_e32 v16, v16, v9
	s_waitcnt vmcnt(4)
	v_add_u32_e32 v16, v16, v10
	s_waitcnt vmcnt(3)
	v_add_u32_e32 v16, v16, v11
	s_waitcnt vmcnt(2)
	v_add_u32_e32 v16, v16, v12
	s_waitcnt vmcnt(1)
	v_add_u32_e32 v16, v16, v13
	s_waitcnt vmcnt(0)
	v_add_u32_e32 v16, v16, v14
	v_cmp_eq_u32_e32 vcc, s57, v16
	s_cbranch_vccnz .LBB0_235
	s_and_b32 s40, s46, 0xff
	s_cmp_eq_u32 s40, 0
	s_mov_b64 s[40:41], -1
	s_mov_b64 s[44:45], -1
	s_nop 0
	s_cbranch_scc1 .LBB0_240
	s_and_b64 vcc, exec, s[44:45]
	s_cbranch_vccz .LBB0_235

.LBB0_271:
	s_and_b32 s18, s22, 0xff
	s_mov_b64 s[16:17], -1
	s_cmp_lg_u32 s18, 0
	s_mov_b64 s[20:21], -1
	s_nop 0
	s_cbranch_scc0 .LBB0_274
	s_and_b64 vcc, exec, s[20:21]
	s_cbranch_vccz .LBB0_270
